# fused residual epilogue second pass: H stores widened with v_permlane16_swap pairs (32 dwordx2 with 32-byte row segments -> 16 dwordx4 with 64-byte segments)
# baseline (speedup 1.0000x reference)
; __device__ __forceinline__ unsigned cvt_pk_bf16(float lo, float hi) { unsigned r; asm volatile("v_cvt_pk_bf16_f32 %0, %1, %2" : "=v"(r) : "v"(lo), "v"(hi)); return r; }
;     __device__ __forceinline__ void fused(f32x4 (&acc)[2][2][4][2], const Unit& u, int wr, int wc, int fr, int fq, ldsp lds, int wid, int lane) const {
;     ...
;         for (int bj = 0; bj < 2; ++bj)
; #pragma unroll
;             for (int n = 0; n < 2; ++n) { const int c = colt + bj * HALF + n * 16;
;                 f32x4 gc = *(const f32x4*)(gain + c), sh = (f32x4){0.f, 0.f, 0.f, 0.f};
;                 if (!fin) { gc = gc * (*(const f32x4*)(mb + scoff + c) + 1.0f); sh = *(const f32x4*)(mb + shoff + c); }
; #pragma unroll
;                 for (int ai = 0; ai < 2; ++ai)
; #pragma unroll
;                     for (int m = 0; m < 4; ++m) { const int r = ai * HALF + wr * 64 + m * 16 + fr; const float rs = Sx[r];
;                         const f32x4 y = (acc[ai][bj][m][n] * rs) * gc + sh;
;                         if (fin) *(f32x4*)(xd + (size_t)(rowt + r) * D + c) = y;
;                         else { u32x2 w; w.x = cvt_pk_bf16(y[0], y[1]); w.y = cvt_pk_bf16(y[2], y[3]); *(u32x2*)(H + (size_t)(rowt + r) * D + c) = w; } } }
.LBB0_452:
	v_lshl_add_u32 v96, v148, 2, 0
	ds_read_b32 v118, v96 offset:4096
	s_mov_b64 s[6:7], -1
	s_and_b64 vcc, exec, s[84:85]
	s_waitcnt lgkmcnt(0)
	v_pk_mul_f32 v[138:139], v[138:139], v[118:119] op_sel_hi:[1,0]
	v_pk_mul_f32 v[118:119], v[140:141], v[118:119] op_sel_hi:[1,0]
	s_waitcnt vmcnt(0)
	v_pk_fma_f32 v[120:121], v[104:105], v[118:119], v[112:113]
	v_pk_fma_f32 v[118:119], v[102:103], v[138:139], v[110:111]
	s_cbranch_vccz .LBB0_454
	v_add_u32_e32 v140, s8, v148
	v_ashrrev_i32_e32 v141, 31, v140
	v_readlane_b32 s4, v254, 35
	v_lshlrev_b64 v[140:141], 11, v[140:141]
	v_readlane_b32 s5, v254, 36
	v_cvt_pk_bf16_f32 v138, v118, v119
	v_cvt_pk_bf16_f32 v139, v120, v121
	s_mov_b64 s[6:7], 0
	s_nop 0
	v_lshl_add_u64 v[140:141], s[4:5], 0, v[140:141]
	v_lshl_add_u64 v[140:141], v[142:143], 1, v[140:141]
	v_mov_b64_e32 v[238:239], v[138:139]

; __device__ __forceinline__ unsigned cvt_pk_bf16(float lo, float hi) { unsigned r; asm volatile("v_cvt_pk_bf16_f32 %0, %1, %2" : "=v"(r) : "v"(lo), "v"(hi)); return r; }
;     __device__ __forceinline__ void fused(f32x4 (&acc)[2][2][4][2], const Unit& u, int wr, int wc, int fr, int fq, ldsp lds, int wid, int lane) const {
;     ...
;         for (int bj = 0; bj < 2; ++bj)
; #pragma unroll
;             for (int n = 0; n < 2; ++n) { const int c = colt + bj * HALF + n * 16;
;                 f32x4 gc = *(const f32x4*)(gain + c), sh = (f32x4){0.f, 0.f, 0.f, 0.f};
;                 if (!fin) { gc = gc * (*(const f32x4*)(mb + scoff + c) + 1.0f); sh = *(const f32x4*)(mb + shoff + c); }
; #pragma unroll
;                 for (int ai = 0; ai < 2; ++ai)
; #pragma unroll
;                     for (int m = 0; m < 4; ++m) { const int r = ai * HALF + wr * 64 + m * 16 + fr; const float rs = Sx[r];
;                         const f32x4 y = (acc[ai][bj][m][n] * rs) * gc + sh;
;                         if (fin) *(f32x4*)(xd + (size_t)(rowt + r) * D + c) = y;
;                         else { u32x2 w; w.x = cvt_pk_bf16(y[0], y[1]); w.y = cvt_pk_bf16(y[2], y[3]); *(u32x2*)(H + (size_t)(rowt + r) * D + c) = w; } } }
.LBB0_456:
	ds_read_b32 v118, v96 offset:4160
	v_or_b32_e32 v138, 16, v148
	s_mov_b64 s[6:7], -1
	s_and_b64 vcc, exec, s[84:85]
	s_waitcnt lgkmcnt(0)
	v_pk_mul_f32 v[120:121], v[136:137], v[118:119] op_sel_hi:[1,0]
	v_pk_mul_f32 v[118:119], v[134:135], v[118:119] op_sel_hi:[1,0]
	v_pk_fma_f32 v[120:121], v[104:105], v[120:121], v[112:113]
	v_pk_fma_f32 v[118:119], v[102:103], v[118:119], v[110:111]
	s_cbranch_vccz .LBB0_458
	v_add_u32_e32 v136, s8, v138
	v_ashrrev_i32_e32 v137, 31, v136
	v_readlane_b32 s4, v254, 35
	v_lshlrev_b64 v[136:137], 11, v[136:137]
	v_readlane_b32 s5, v254, 36
	v_cvt_pk_bf16_f32 v134, v118, v119
	v_cvt_pk_bf16_f32 v135, v120, v121
	s_mov_b64 s[6:7], 0
	s_nop 0
	v_lshl_add_u64 v[136:137], s[4:5], 0, v[136:137]
	v_lshl_add_u64 v[136:137], v[142:143], 1, v[136:137]
	v_mov_b64_e32 v[242:243], v[134:135]

; __device__ __forceinline__ unsigned cvt_pk_bf16(float lo, float hi) { unsigned r; asm volatile("v_cvt_pk_bf16_f32 %0, %1, %2" : "=v"(r) : "v"(lo), "v"(hi)); return r; }
;     __device__ __forceinline__ void fused(f32x4 (&acc)[2][2][4][2], const Unit& u, int wr, int wc, int fr, int fq, ldsp lds, int wid, int lane) const {
;     ...
;         for (int bj = 0; bj < 2; ++bj)
; #pragma unroll
;             for (int n = 0; n < 2; ++n) { const int c = colt + bj * HALF + n * 16;
;                 f32x4 gc = *(const f32x4*)(gain + c), sh = (f32x4){0.f, 0.f, 0.f, 0.f};
;                 if (!fin) { gc = gc * (*(const f32x4*)(mb + scoff + c) + 1.0f); sh = *(const f32x4*)(mb + shoff + c); }
; #pragma unroll
;                 for (int ai = 0; ai < 2; ++ai)
; #pragma unroll
;                     for (int m = 0; m < 4; ++m) { const int r = ai * HALF + wr * 64 + m * 16 + fr; const float rs = Sx[r];
;                         const f32x4 y = (acc[ai][bj][m][n] * rs) * gc + sh;
;                         if (fin) *(f32x4*)(xd + (size_t)(rowt + r) * D + c) = y;
;                         else { u32x2 w; w.x = cvt_pk_bf16(y[0], y[1]); w.y = cvt_pk_bf16(y[2], y[3]); *(u32x2*)(H + (size_t)(rowt + r) * D + c) = w; } } }
.LBB0_460:
	ds_read_b32 v118, v96 offset:4224
	v_or_b32_e32 v134, 32, v148
	s_mov_b64 s[6:7], -1
	s_and_b64 vcc, exec, s[84:85]
	s_waitcnt lgkmcnt(0)
	v_pk_mul_f32 v[120:121], v[132:133], v[118:119] op_sel_hi:[1,0]
	v_pk_mul_f32 v[118:119], v[130:131], v[118:119] op_sel_hi:[1,0]
	v_pk_fma_f32 v[120:121], v[104:105], v[120:121], v[112:113]
	v_pk_fma_f32 v[118:119], v[102:103], v[118:119], v[110:111]
	s_cbranch_vccz .LBB0_462
	v_add_u32_e32 v132, s8, v134
	v_ashrrev_i32_e32 v133, 31, v132
	v_readlane_b32 s4, v254, 35
	v_lshlrev_b64 v[132:133], 11, v[132:133]
	v_readlane_b32 s5, v254, 36
	v_cvt_pk_bf16_f32 v130, v118, v119
	v_cvt_pk_bf16_f32 v131, v120, v121
	s_mov_b64 s[6:7], 0
	s_nop 0
	v_lshl_add_u64 v[132:133], s[4:5], 0, v[132:133]
	v_lshl_add_u64 v[132:133], v[142:143], 1, v[132:133]
	v_mov_b64_e32 v[246:247], v[130:131]

; __device__ __forceinline__ unsigned cvt_pk_bf16(float lo, float hi) { unsigned r; asm volatile("v_cvt_pk_bf16_f32 %0, %1, %2" : "=v"(r) : "v"(lo), "v"(hi)); return r; }
;     __device__ __forceinline__ void fused(f32x4 (&acc)[2][2][4][2], const Unit& u, int wr, int wc, int fr, int fq, ldsp lds, int wid, int lane) const {
;     ...
;         for (int bj = 0; bj < 2; ++bj)
; #pragma unroll
;             for (int n = 0; n < 2; ++n) { const int c = colt + bj * HALF + n * 16;
;                 f32x4 gc = *(const f32x4*)(gain + c), sh = (f32x4){0.f, 0.f, 0.f, 0.f};
;                 if (!fin) { gc = gc * (*(const f32x4*)(mb + scoff + c) + 1.0f); sh = *(const f32x4*)(mb + shoff + c); }
; #pragma unroll
;                 for (int ai = 0; ai < 2; ++ai)
; #pragma unroll
;                     for (int m = 0; m < 4; ++m) { const int r = ai * HALF + wr * 64 + m * 16 + fr; const float rs = Sx[r];
;                         const f32x4 y = (acc[ai][bj][m][n] * rs) * gc + sh;
;                         if (fin) *(f32x4*)(xd + (size_t)(rowt + r) * D + c) = y;
;                         else { u32x2 w; w.x = cvt_pk_bf16(y[0], y[1]); w.y = cvt_pk_bf16(y[2], y[3]); *(u32x2*)(H + (size_t)(rowt + r) * D + c) = w; } } }
.LBB0_464:
	ds_read_b32 v118, v96 offset:4288
	v_or_b32_e32 v130, 48, v148
	s_mov_b64 s[6:7], -1
	s_and_b64 vcc, exec, s[84:85]
	s_waitcnt lgkmcnt(0)
	v_pk_mul_f32 v[120:121], v[128:129], v[118:119] op_sel_hi:[1,0]
	v_pk_mul_f32 v[118:119], v[126:127], v[118:119] op_sel_hi:[1,0]
	v_pk_fma_f32 v[120:121], v[104:105], v[120:121], v[112:113]
	v_pk_fma_f32 v[118:119], v[102:103], v[118:119], v[110:111]
	s_cbranch_vccz .LBB0_466
	v_add_u32_e32 v128, s8, v130
	v_ashrrev_i32_e32 v129, 31, v128
	v_readlane_b32 s4, v254, 35
	v_lshlrev_b64 v[128:129], 11, v[128:129]
	v_readlane_b32 s5, v254, 36
	v_cvt_pk_bf16_f32 v126, v118, v119
	v_cvt_pk_bf16_f32 v127, v120, v121
	s_mov_b64 s[6:7], 0
	s_nop 0
	v_lshl_add_u64 v[128:129], s[4:5], 0, v[128:129]
	v_lshl_add_u64 v[128:129], v[142:143], 1, v[128:129]
	v_mov_b64_e32 v[250:251], v[126:127]

; __device__ __forceinline__ unsigned cvt_pk_bf16(float lo, float hi) { unsigned r; asm volatile("v_cvt_pk_bf16_f32 %0, %1, %2" : "=v"(r) : "v"(lo), "v"(hi)); return r; }
;     __device__ __forceinline__ void fused(f32x4 (&acc)[2][2][4][2], const Unit& u, int wr, int wc, int fr, int fq, ldsp lds, int wid, int lane) const {
;     ...
;         for (int bj = 0; bj < 2; ++bj)
; #pragma unroll
;             for (int n = 0; n < 2; ++n) { const int c = colt + bj * HALF + n * 16;
;                 f32x4 gc = *(const f32x4*)(gain + c), sh = (f32x4){0.f, 0.f, 0.f, 0.f};
;                 if (!fin) { gc = gc * (*(const f32x4*)(mb + scoff + c) + 1.0f); sh = *(const f32x4*)(mb + shoff + c); }
; #pragma unroll
;                 for (int ai = 0; ai < 2; ++ai)
; #pragma unroll
;                     for (int m = 0; m < 4; ++m) { const int r = ai * HALF + wr * 64 + m * 16 + fr; const float rs = Sx[r];
;                         const f32x4 y = (acc[ai][bj][m][n] * rs) * gc + sh;
;                         if (fin) *(f32x4*)(xd + (size_t)(rowt + r) * D + c) = y;
;                         else { u32x2 w; w.x = cvt_pk_bf16(y[0], y[1]); w.y = cvt_pk_bf16(y[2], y[3]); *(u32x2*)(H + (size_t)(rowt + r) * D + c) = w; } } }
.LBB0_468:
	ds_read_b32 v118, v96 offset:4608
	v_add_u32_e32 v126, 0x80, v148
	s_mov_b64 s[6:7], -1
	s_and_b64 vcc, exec, s[84:85]
	s_waitcnt lgkmcnt(0)
	v_pk_mul_f32 v[120:121], v[124:125], v[118:119] op_sel_hi:[1,0]
	v_pk_mul_f32 v[118:119], v[122:123], v[118:119] op_sel_hi:[1,0]
	v_pk_fma_f32 v[120:121], v[104:105], v[120:121], v[112:113]
	v_pk_fma_f32 v[118:119], v[102:103], v[118:119], v[110:111]
	s_cbranch_vccz .LBB0_470
	v_add_u32_e32 v124, s8, v126
	v_ashrrev_i32_e32 v125, 31, v124
	v_readlane_b32 s4, v254, 35
	v_lshlrev_b64 v[124:125], 11, v[124:125]
	v_readlane_b32 s5, v254, 36
	v_cvt_pk_bf16_f32 v122, v118, v119
	v_cvt_pk_bf16_f32 v123, v120, v121
	s_mov_b64 s[6:7], 0
	s_nop 0
	v_lshl_add_u64 v[124:125], s[4:5], 0, v[124:125]
	v_lshl_add_u64 v[124:125], v[142:143], 1, v[124:125]
	v_mov_b64_e32 v[202:203], v[122:123]

; __device__ __forceinline__ unsigned cvt_pk_bf16(float lo, float hi) { unsigned r; asm volatile("v_cvt_pk_bf16_f32 %0, %1, %2" : "=v"(r) : "v"(lo), "v"(hi)); return r; }
;     __device__ __forceinline__ void fused(f32x4 (&acc)[2][2][4][2], const Unit& u, int wr, int wc, int fr, int fq, ldsp lds, int wid, int lane) const {
;     ...
;         for (int bj = 0; bj < 2; ++bj)
; #pragma unroll
;             for (int n = 0; n < 2; ++n) { const int c = colt + bj * HALF + n * 16;
;                 f32x4 gc = *(const f32x4*)(gain + c), sh = (f32x4){0.f, 0.f, 0.f, 0.f};
;                 if (!fin) { gc = gc * (*(const f32x4*)(mb + scoff + c) + 1.0f); sh = *(const f32x4*)(mb + shoff + c); }
; #pragma unroll
;                 for (int ai = 0; ai < 2; ++ai)
; #pragma unroll
;                     for (int m = 0; m < 4; ++m) { const int r = ai * HALF + wr * 64 + m * 16 + fr; const float rs = Sx[r];
;                         const f32x4 y = (acc[ai][bj][m][n] * rs) * gc + sh;
;                         if (fin) *(f32x4*)(xd + (size_t)(rowt + r) * D + c) = y;
;                         else { u32x2 w; w.x = cvt_pk_bf16(y[0], y[1]); w.y = cvt_pk_bf16(y[2], y[3]); *(u32x2*)(H + (size_t)(rowt + r) * D + c) = w; } } }
.LBB0_472:
	ds_read_b32 v120, v96 offset:4672
	s_nop 0
	v_add_u32_e32 v118, 0x90, v148
	s_mov_b64 s[6:7], -1
	s_and_b64 vcc, exec, s[84:85]
	s_waitcnt lgkmcnt(0)
	v_pk_mul_f32 v[116:117], v[116:117], v[120:121] op_sel_hi:[1,0]
	v_pk_mul_f32 v[114:115], v[114:115], v[120:121] op_sel_hi:[1,0]
	v_pk_fma_f32 v[116:117], v[104:105], v[116:117], v[112:113]
	v_pk_fma_f32 v[114:115], v[102:103], v[114:115], v[110:111]
	s_cbranch_vccz .LBB0_474
	v_add_u32_e32 v122, s8, v118
	v_ashrrev_i32_e32 v123, 31, v122
	v_readlane_b32 s4, v254, 35
	v_lshlrev_b64 v[122:123], 11, v[122:123]
	v_readlane_b32 s5, v254, 36
	v_cvt_pk_bf16_f32 v120, v114, v115
	v_cvt_pk_bf16_f32 v121, v116, v117
	s_mov_b64 s[6:7], 0
	s_nop 0
	v_lshl_add_u64 v[122:123], s[4:5], 0, v[122:123]
	v_lshl_add_u64 v[122:123], v[142:143], 1, v[122:123]
	v_mov_b64_e32 v[206:207], v[120:121]

; __device__ __forceinline__ unsigned cvt_pk_bf16(float lo, float hi) { unsigned r; asm volatile("v_cvt_pk_bf16_f32 %0, %1, %2" : "=v"(r) : "v"(lo), "v"(hi)); return r; }
;     __device__ __forceinline__ void fused(f32x4 (&acc)[2][2][4][2], const Unit& u, int wr, int wc, int fr, int fq, ldsp lds, int wid, int lane) const {
;     ...
;         for (int bj = 0; bj < 2; ++bj)
; #pragma unroll
;             for (int n = 0; n < 2; ++n) { const int c = colt + bj * HALF + n * 16;
;                 f32x4 gc = *(const f32x4*)(gain + c), sh = (f32x4){0.f, 0.f, 0.f, 0.f};
;                 if (!fin) { gc = gc * (*(const f32x4*)(mb + scoff + c) + 1.0f); sh = *(const f32x4*)(mb + shoff + c); }
; #pragma unroll
;                 for (int ai = 0; ai < 2; ++ai)
; #pragma unroll
;                     for (int m = 0; m < 4; ++m) { const int r = ai * HALF + wr * 64 + m * 16 + fr; const float rs = Sx[r];
;                         const f32x4 y = (acc[ai][bj][m][n] * rs) * gc + sh;
;                         if (fin) *(f32x4*)(xd + (size_t)(rowt + r) * D + c) = y;
;                         else { u32x2 w; w.x = cvt_pk_bf16(y[0], y[1]); w.y = cvt_pk_bf16(y[2], y[3]); *(u32x2*)(H + (size_t)(rowt + r) * D + c) = w; } } }
.LBB0_476:
	ds_read_b32 v116, v96 offset:4736
	s_nop 0
	v_add_u32_e32 v114, 0xa0, v148
	s_mov_b64 s[6:7], -1
	s_and_b64 vcc, exec, s[84:85]
	s_waitcnt lgkmcnt(0)
	v_pk_mul_f32 v[108:109], v[108:109], v[116:117] op_sel_hi:[1,0]
	v_pk_mul_f32 v[106:107], v[106:107], v[116:117] op_sel_hi:[1,0]
	v_pk_fma_f32 v[108:109], v[104:105], v[108:109], v[112:113]
	v_pk_fma_f32 v[106:107], v[102:103], v[106:107], v[110:111]
	s_cbranch_vccz .LBB0_478
	v_add_u32_e32 v120, s8, v114
	v_ashrrev_i32_e32 v121, 31, v120
	v_readlane_b32 s4, v254, 35
	v_lshlrev_b64 v[120:121], 11, v[120:121]
	v_readlane_b32 s5, v254, 36
	v_cvt_pk_bf16_f32 v116, v106, v107
	v_cvt_pk_bf16_f32 v117, v108, v109
	s_mov_b64 s[6:7], 0
	s_nop 0
	v_lshl_add_u64 v[120:121], s[4:5], 0, v[120:121]
	v_lshl_add_u64 v[120:121], v[142:143], 1, v[120:121]
	v_mov_b64_e32 v[210:211], v[116:117]

; __device__ __forceinline__ unsigned cvt_pk_bf16(float lo, float hi) { unsigned r; asm volatile("v_cvt_pk_bf16_f32 %0, %1, %2" : "=v"(r) : "v"(lo), "v"(hi)); return r; }
;     __device__ __forceinline__ void fused(f32x4 (&acc)[2][2][4][2], const Unit& u, int wr, int wc, int fr, int fq, ldsp lds, int wid, int lane) const {
;     ...
;         for (int bj = 0; bj < 2; ++bj)
; #pragma unroll
;             for (int n = 0; n < 2; ++n) { const int c = colt + bj * HALF + n * 16;
;                 f32x4 gc = *(const f32x4*)(gain + c), sh = (f32x4){0.f, 0.f, 0.f, 0.f};
;                 if (!fin) { gc = gc * (*(const f32x4*)(mb + scoff + c) + 1.0f); sh = *(const f32x4*)(mb + shoff + c); }
; #pragma unroll
;                 for (int ai = 0; ai < 2; ++ai)
; #pragma unroll
;                     for (int m = 0; m < 4; ++m) { const int r = ai * HALF + wr * 64 + m * 16 + fr; const float rs = Sx[r];
;                         const f32x4 y = (acc[ai][bj][m][n] * rs) * gc + sh;
;                         if (fin) *(f32x4*)(xd + (size_t)(rowt + r) * D + c) = y;
;                         else { u32x2 w; w.x = cvt_pk_bf16(y[0], y[1]); w.y = cvt_pk_bf16(y[2], y[3]); *(u32x2*)(H + (size_t)(rowt + r) * D + c) = w; } } }
.LBB0_480:
	ds_read_b32 v108, v96 offset:4800
	s_nop 0
	v_add_u32_e32 v106, 0xb0, v148
	s_mov_b64 s[6:7], -1
	s_and_b64 vcc, exec, s[84:85]
	s_waitcnt lgkmcnt(0)
	v_pk_mul_f32 v[100:101], v[100:101], v[108:109] op_sel_hi:[1,0]
	v_pk_mul_f32 v[98:99], v[98:99], v[108:109] op_sel_hi:[1,0]
	v_pk_fma_f32 v[100:101], v[104:105], v[100:101], v[112:113]
	v_pk_fma_f32 v[98:99], v[102:103], v[98:99], v[110:111]
	s_cbranch_vccz .LBB0_484
	v_add_u32_e32 v104, s8, v106
	v_ashrrev_i32_e32 v105, 31, v104
	v_readlane_b32 s4, v254, 35
	v_lshlrev_b64 v[104:105], 11, v[104:105]
	v_readlane_b32 s5, v254, 36
	v_cvt_pk_bf16_f32 v102, v98, v99
	v_cvt_pk_bf16_f32 v103, v100, v101
	s_nop 1
	v_lshl_add_u64 v[104:105], s[4:5], 0, v[104:105]
	v_lshl_add_u64 v[104:105], v[142:143], 1, v[104:105]
	v_mov_b64_e32 v[190:191], v[102:103]
	s_cbranch_execz .LBB0_485

; __device__ __forceinline__ unsigned cvt_pk_bf16(float lo, float hi) { unsigned r; asm volatile("v_cvt_pk_bf16_f32 %0, %1, %2" : "=v"(r) : "v"(lo), "v"(hi)); return r; }
;     __device__ __forceinline__ void fused(f32x4 (&acc)[2][2][4][2], const Unit& u, int wr, int wc, int fr, int fq, ldsp lds, int wid, int lane) const {
;     ...
;         for (int bj = 0; bj < 2; ++bj)
; #pragma unroll
;             for (int n = 0; n < 2; ++n) { const int c = colt + bj * HALF + n * 16;
;                 f32x4 gc = *(const f32x4*)(gain + c), sh = (f32x4){0.f, 0.f, 0.f, 0.f};
;                 if (!fin) { gc = gc * (*(const f32x4*)(mb + scoff + c) + 1.0f); sh = *(const f32x4*)(mb + shoff + c); }
; #pragma unroll
;                 for (int ai = 0; ai < 2; ++ai)
; #pragma unroll
;                     for (int m = 0; m < 4; ++m) { const int r = ai * HALF + wr * 64 + m * 16 + fr; const float rs = Sx[r];
;                         const f32x4 y = (acc[ai][bj][m][n] * rs) * gc + sh;
;                         if (fin) *(f32x4*)(xd + (size_t)(rowt + r) * D + c) = y;
;                         else { u32x2 w; w.x = cvt_pk_bf16(y[0], y[1]); w.y = cvt_pk_bf16(y[2], y[3]); *(u32x2*)(H + (size_t)(rowt + r) * D + c) = w; } } }
.LBB0_487:
	ds_read_b32 v108, v96 offset:4096
	s_mov_b64 s[6:7], -1
	s_and_b64 vcc, exec, s[84:85]
	s_waitcnt lgkmcnt(0)
	v_pk_mul_f32 v[94:95], v[94:95], v[108:109] op_sel_hi:[1,0]
	v_pk_mul_f32 v[92:93], v[92:93], v[108:109] op_sel_hi:[1,0]
	v_pk_fma_f32 v[94:95], v[100:101], v[94:95], v[104:105]
	v_pk_fma_f32 v[92:93], v[98:99], v[92:93], v[102:103]
	s_cbranch_vccz .LBB0_489
	v_add_u32_e32 v110, s8, v148
	v_ashrrev_i32_e32 v111, 31, v110
	v_readlane_b32 s4, v254, 35
	v_lshlrev_b64 v[110:111], 11, v[110:111]
	v_readlane_b32 s5, v254, 36
	v_cvt_pk_bf16_f32 v108, v92, v93
	v_cvt_pk_bf16_f32 v109, v94, v95
	s_mov_b64 s[6:7], 0
	s_nop 0
	v_lshl_add_u64 v[110:111], s[4:5], 0, v[110:111]
	v_lshl_add_u64 v[110:111], v[142:143], 1, v[110:111]
	v_mov_b64_e32 v[240:241], v[108:109]
	v_bfe_u32 v194, v196, 4, 1
	v_mov_b32_e32 v195, 0
	v_mul_u32_u24_e32 v194, 24, v194
	v_lshl_add_u64 v[110:111], v[110:111], 0, v[194:195]
	v_permlane16_swap_b32_e32 v238, v240
	v_permlane16_swap_b32_e32 v239, v241
	global_store_dwordx4 v[110:111], v[238:241], off

; __device__ __forceinline__ unsigned cvt_pk_bf16(float lo, float hi) { unsigned r; asm volatile("v_cvt_pk_bf16_f32 %0, %1, %2" : "=v"(r) : "v"(lo), "v"(hi)); return r; }
;     __device__ __forceinline__ void fused(f32x4 (&acc)[2][2][4][2], const Unit& u, int wr, int wc, int fr, int fq, ldsp lds, int wid, int lane) const {
;     ...
;         for (int bj = 0; bj < 2; ++bj)
; #pragma unroll
;             for (int n = 0; n < 2; ++n) { const int c = colt + bj * HALF + n * 16;
;                 f32x4 gc = *(const f32x4*)(gain + c), sh = (f32x4){0.f, 0.f, 0.f, 0.f};
;                 if (!fin) { gc = gc * (*(const f32x4*)(mb + scoff + c) + 1.0f); sh = *(const f32x4*)(mb + shoff + c); }
; #pragma unroll
;                 for (int ai = 0; ai < 2; ++ai)
; #pragma unroll
;                     for (int m = 0; m < 4; ++m) { const int r = ai * HALF + wr * 64 + m * 16 + fr; const float rs = Sx[r];
;                         const f32x4 y = (acc[ai][bj][m][n] * rs) * gc + sh;
;                         if (fin) *(f32x4*)(xd + (size_t)(rowt + r) * D + c) = y;
;                         else { u32x2 w; w.x = cvt_pk_bf16(y[0], y[1]); w.y = cvt_pk_bf16(y[2], y[3]); *(u32x2*)(H + (size_t)(rowt + r) * D + c) = w; } } }
.LBB0_491:
	ds_read_b32 v92, v96 offset:4160
	s_mov_b64 s[6:7], -1
	s_and_b64 vcc, exec, s[84:85]
	s_waitcnt lgkmcnt(0)
	v_pk_mul_f32 v[90:91], v[90:91], v[92:93] op_sel_hi:[1,0]
	v_pk_mul_f32 v[88:89], v[88:89], v[92:93] op_sel_hi:[1,0]
	v_pk_fma_f32 v[90:91], v[100:101], v[90:91], v[104:105]
	v_pk_fma_f32 v[88:89], v[98:99], v[88:89], v[102:103]
	s_cbranch_vccz .LBB0_493
	v_add_u32_e32 v94, s8, v138
	v_ashrrev_i32_e32 v95, 31, v94
	v_readlane_b32 s4, v254, 35
	v_lshlrev_b64 v[94:95], 11, v[94:95]
	v_readlane_b32 s5, v254, 36
	v_cvt_pk_bf16_f32 v92, v88, v89
	v_cvt_pk_bf16_f32 v93, v90, v91
	s_mov_b64 s[6:7], 0
	s_nop 0
	v_lshl_add_u64 v[94:95], s[4:5], 0, v[94:95]
	v_lshl_add_u64 v[94:95], v[142:143], 1, v[94:95]
	v_mov_b64_e32 v[244:245], v[92:93]
	v_bfe_u32 v194, v196, 4, 1
	v_mov_b32_e32 v195, 0
	v_mul_u32_u24_e32 v194, 24, v194
	v_lshl_add_u64 v[94:95], v[94:95], 0, v[194:195]
	v_permlane16_swap_b32_e32 v242, v244
	v_permlane16_swap_b32_e32 v243, v245
	global_store_dwordx4 v[94:95], v[242:245], off

; __device__ __forceinline__ unsigned cvt_pk_bf16(float lo, float hi) { unsigned r; asm volatile("v_cvt_pk_bf16_f32 %0, %1, %2" : "=v"(r) : "v"(lo), "v"(hi)); return r; }
;     __device__ __forceinline__ void fused(f32x4 (&acc)[2][2][4][2], const Unit& u, int wr, int wc, int fr, int fq, ldsp lds, int wid, int lane) const {
;     ...
;         for (int bj = 0; bj < 2; ++bj)
; #pragma unroll
;             for (int n = 0; n < 2; ++n) { const int c = colt + bj * HALF + n * 16;
;                 f32x4 gc = *(const f32x4*)(gain + c), sh = (f32x4){0.f, 0.f, 0.f, 0.f};
;                 if (!fin) { gc = gc * (*(const f32x4*)(mb + scoff + c) + 1.0f); sh = *(const f32x4*)(mb + shoff + c); }
; #pragma unroll
;                 for (int ai = 0; ai < 2; ++ai)
; #pragma unroll
;                     for (int m = 0; m < 4; ++m) { const int r = ai * HALF + wr * 64 + m * 16 + fr; const float rs = Sx[r];
;                         const f32x4 y = (acc[ai][bj][m][n] * rs) * gc + sh;
;                         if (fin) *(f32x4*)(xd + (size_t)(rowt + r) * D + c) = y;
;                         else { u32x2 w; w.x = cvt_pk_bf16(y[0], y[1]); w.y = cvt_pk_bf16(y[2], y[3]); *(u32x2*)(H + (size_t)(rowt + r) * D + c) = w; } } }
.LBB0_495:
	ds_read_b32 v88, v96 offset:4224
	s_mov_b64 s[6:7], -1
	s_and_b64 vcc, exec, s[84:85]
	s_waitcnt lgkmcnt(0)
	v_pk_mul_f32 v[86:87], v[86:87], v[88:89] op_sel_hi:[1,0]
	v_pk_mul_f32 v[84:85], v[84:85], v[88:89] op_sel_hi:[1,0]
	v_pk_fma_f32 v[86:87], v[100:101], v[86:87], v[104:105]
	v_pk_fma_f32 v[84:85], v[98:99], v[84:85], v[102:103]
	s_cbranch_vccz .LBB0_497
	v_add_u32_e32 v90, s8, v134
	v_ashrrev_i32_e32 v91, 31, v90
	v_readlane_b32 s4, v254, 35
	v_lshlrev_b64 v[90:91], 11, v[90:91]
	v_readlane_b32 s5, v254, 36
	v_cvt_pk_bf16_f32 v88, v84, v85
	v_cvt_pk_bf16_f32 v89, v86, v87
	s_mov_b64 s[6:7], 0
	s_nop 0
	v_lshl_add_u64 v[90:91], s[4:5], 0, v[90:91]
	v_lshl_add_u64 v[90:91], v[142:143], 1, v[90:91]
	v_mov_b64_e32 v[248:249], v[88:89]
	v_bfe_u32 v194, v196, 4, 1
	v_mov_b32_e32 v195, 0
	v_mul_u32_u24_e32 v194, 24, v194
	v_lshl_add_u64 v[90:91], v[90:91], 0, v[194:195]
	v_permlane16_swap_b32_e32 v246, v248
	v_permlane16_swap_b32_e32 v247, v249
	global_store_dwordx4 v[90:91], v[246:249], off

; __device__ __forceinline__ unsigned cvt_pk_bf16(float lo, float hi) { unsigned r; asm volatile("v_cvt_pk_bf16_f32 %0, %1, %2" : "=v"(r) : "v"(lo), "v"(hi)); return r; }
;     __device__ __forceinline__ void fused(f32x4 (&acc)[2][2][4][2], const Unit& u, int wr, int wc, int fr, int fq, ldsp lds, int wid, int lane) const {
;     ...
;         for (int bj = 0; bj < 2; ++bj)
; #pragma unroll
;             for (int n = 0; n < 2; ++n) { const int c = colt + bj * HALF + n * 16;
;                 f32x4 gc = *(const f32x4*)(gain + c), sh = (f32x4){0.f, 0.f, 0.f, 0.f};
;                 if (!fin) { gc = gc * (*(const f32x4*)(mb + scoff + c) + 1.0f); sh = *(const f32x4*)(mb + shoff + c); }
; #pragma unroll
;                 for (int ai = 0; ai < 2; ++ai)
; #pragma unroll
;                     for (int m = 0; m < 4; ++m) { const int r = ai * HALF + wr * 64 + m * 16 + fr; const float rs = Sx[r];
;                         const f32x4 y = (acc[ai][bj][m][n] * rs) * gc + sh;
;                         if (fin) *(f32x4*)(xd + (size_t)(rowt + r) * D + c) = y;
;                         else { u32x2 w; w.x = cvt_pk_bf16(y[0], y[1]); w.y = cvt_pk_bf16(y[2], y[3]); *(u32x2*)(H + (size_t)(rowt + r) * D + c) = w; } } }
.LBB0_499:
	ds_read_b32 v84, v96 offset:4288
	s_mov_b64 s[6:7], -1
	s_and_b64 vcc, exec, s[84:85]
	s_waitcnt lgkmcnt(0)
	v_pk_mul_f32 v[82:83], v[82:83], v[84:85] op_sel_hi:[1,0]
	v_pk_mul_f32 v[80:81], v[80:81], v[84:85] op_sel_hi:[1,0]
	v_pk_fma_f32 v[82:83], v[100:101], v[82:83], v[104:105]
	v_pk_fma_f32 v[80:81], v[98:99], v[80:81], v[102:103]
	s_cbranch_vccz .LBB0_501
	v_add_u32_e32 v86, s8, v130
	v_ashrrev_i32_e32 v87, 31, v86
	v_readlane_b32 s4, v254, 35
	v_lshlrev_b64 v[86:87], 11, v[86:87]
	v_readlane_b32 s5, v254, 36
	v_cvt_pk_bf16_f32 v84, v80, v81
	v_cvt_pk_bf16_f32 v85, v82, v83
	s_mov_b64 s[6:7], 0
	s_nop 0
	v_lshl_add_u64 v[86:87], s[4:5], 0, v[86:87]
	v_lshl_add_u64 v[86:87], v[142:143], 1, v[86:87]
	v_mov_b64_e32 v[252:253], v[84:85]
	v_bfe_u32 v194, v196, 4, 1
	v_mov_b32_e32 v195, 0
	v_mul_u32_u24_e32 v194, 24, v194
	v_lshl_add_u64 v[86:87], v[86:87], 0, v[194:195]
	v_permlane16_swap_b32_e32 v250, v252
	v_permlane16_swap_b32_e32 v251, v253
	global_store_dwordx4 v[86:87], v[250:253], off

; __device__ __forceinline__ unsigned cvt_pk_bf16(float lo, float hi) { unsigned r; asm volatile("v_cvt_pk_bf16_f32 %0, %1, %2" : "=v"(r) : "v"(lo), "v"(hi)); return r; }
;     __device__ __forceinline__ void fused(f32x4 (&acc)[2][2][4][2], const Unit& u, int wr, int wc, int fr, int fq, ldsp lds, int wid, int lane) const {
;     ...
;         for (int bj = 0; bj < 2; ++bj)
; #pragma unroll
;             for (int n = 0; n < 2; ++n) { const int c = colt + bj * HALF + n * 16;
;                 f32x4 gc = *(const f32x4*)(gain + c), sh = (f32x4){0.f, 0.f, 0.f, 0.f};
;                 if (!fin) { gc = gc * (*(const f32x4*)(mb + scoff + c) + 1.0f); sh = *(const f32x4*)(mb + shoff + c); }
; #pragma unroll
;                 for (int ai = 0; ai < 2; ++ai)
; #pragma unroll
;                     for (int m = 0; m < 4; ++m) { const int r = ai * HALF + wr * 64 + m * 16 + fr; const float rs = Sx[r];
;                         const f32x4 y = (acc[ai][bj][m][n] * rs) * gc + sh;
;                         if (fin) *(f32x4*)(xd + (size_t)(rowt + r) * D + c) = y;
;                         else { u32x2 w; w.x = cvt_pk_bf16(y[0], y[1]); w.y = cvt_pk_bf16(y[2], y[3]); *(u32x2*)(H + (size_t)(rowt + r) * D + c) = w; } } }
.LBB0_503:
	ds_read_b32 v80, v96 offset:4608
	s_mov_b64 s[6:7], -1
	s_and_b64 vcc, exec, s[84:85]
	s_waitcnt lgkmcnt(0)
	v_pk_mul_f32 v[78:79], v[78:79], v[80:81] op_sel_hi:[1,0]
	v_pk_mul_f32 v[76:77], v[76:77], v[80:81] op_sel_hi:[1,0]
	v_pk_fma_f32 v[78:79], v[100:101], v[78:79], v[104:105]
	v_pk_fma_f32 v[76:77], v[98:99], v[76:77], v[102:103]
	s_cbranch_vccz .LBB0_505
	v_add_u32_e32 v82, s8, v126
	v_ashrrev_i32_e32 v83, 31, v82
	v_readlane_b32 s4, v254, 35
	v_lshlrev_b64 v[82:83], 11, v[82:83]
	v_readlane_b32 s5, v254, 36
	v_cvt_pk_bf16_f32 v80, v76, v77
	v_cvt_pk_bf16_f32 v81, v78, v79
	s_mov_b64 s[6:7], 0
	s_nop 0
	v_lshl_add_u64 v[82:83], s[4:5], 0, v[82:83]
	v_lshl_add_u64 v[82:83], v[142:143], 1, v[82:83]
	v_mov_b64_e32 v[204:205], v[80:81]
	v_bfe_u32 v194, v196, 4, 1
	v_mov_b32_e32 v195, 0
	v_mul_u32_u24_e32 v194, 24, v194
	v_lshl_add_u64 v[82:83], v[82:83], 0, v[194:195]
	v_permlane16_swap_b32_e32 v202, v204
	v_permlane16_swap_b32_e32 v203, v205
	global_store_dwordx4 v[82:83], v[202:205], off

; __device__ __forceinline__ unsigned cvt_pk_bf16(float lo, float hi) { unsigned r; asm volatile("v_cvt_pk_bf16_f32 %0, %1, %2" : "=v"(r) : "v"(lo), "v"(hi)); return r; }
;     __device__ __forceinline__ void fused(f32x4 (&acc)[2][2][4][2], const Unit& u, int wr, int wc, int fr, int fq, ldsp lds, int wid, int lane) const {
;     ...
;         for (int bj = 0; bj < 2; ++bj)
; #pragma unroll
;             for (int n = 0; n < 2; ++n) { const int c = colt + bj * HALF + n * 16;
;                 f32x4 gc = *(const f32x4*)(gain + c), sh = (f32x4){0.f, 0.f, 0.f, 0.f};
;                 if (!fin) { gc = gc * (*(const f32x4*)(mb + scoff + c) + 1.0f); sh = *(const f32x4*)(mb + shoff + c); }
; #pragma unroll
;                 for (int ai = 0; ai < 2; ++ai)
; #pragma unroll
;                     for (int m = 0; m < 4; ++m) { const int r = ai * HALF + wr * 64 + m * 16 + fr; const float rs = Sx[r];
;                         const f32x4 y = (acc[ai][bj][m][n] * rs) * gc + sh;
;                         if (fin) *(f32x4*)(xd + (size_t)(rowt + r) * D + c) = y;
;                         else { u32x2 w; w.x = cvt_pk_bf16(y[0], y[1]); w.y = cvt_pk_bf16(y[2], y[3]); *(u32x2*)(H + (size_t)(rowt + r) * D + c) = w; } } }
.LBB0_507:
	ds_read_b32 v76, v96 offset:4672
	s_mov_b64 s[6:7], -1
	s_and_b64 vcc, exec, s[84:85]
	s_waitcnt lgkmcnt(0)
	v_pk_mul_f32 v[74:75], v[74:75], v[76:77] op_sel_hi:[1,0]
	v_pk_mul_f32 v[72:73], v[72:73], v[76:77] op_sel_hi:[1,0]
	v_pk_fma_f32 v[74:75], v[100:101], v[74:75], v[104:105]
	v_pk_fma_f32 v[72:73], v[98:99], v[72:73], v[102:103]
	s_cbranch_vccz .LBB0_509
	v_add_u32_e32 v78, s8, v118
	v_ashrrev_i32_e32 v79, 31, v78
	v_readlane_b32 s4, v254, 35
	v_lshlrev_b64 v[78:79], 11, v[78:79]
	v_readlane_b32 s5, v254, 36
	v_cvt_pk_bf16_f32 v76, v72, v73
	v_cvt_pk_bf16_f32 v77, v74, v75
	s_mov_b64 s[6:7], 0
	s_nop 0
	v_lshl_add_u64 v[78:79], s[4:5], 0, v[78:79]
	v_lshl_add_u64 v[78:79], v[142:143], 1, v[78:79]
	v_mov_b64_e32 v[208:209], v[76:77]
	v_bfe_u32 v194, v196, 4, 1
	v_mov_b32_e32 v195, 0
	v_mul_u32_u24_e32 v194, 24, v194
	v_lshl_add_u64 v[78:79], v[78:79], 0, v[194:195]
	v_permlane16_swap_b32_e32 v206, v208
	v_permlane16_swap_b32_e32 v207, v209
	global_store_dwordx4 v[78:79], v[206:209], off

; __device__ __forceinline__ unsigned cvt_pk_bf16(float lo, float hi) { unsigned r; asm volatile("v_cvt_pk_bf16_f32 %0, %1, %2" : "=v"(r) : "v"(lo), "v"(hi)); return r; }
;     __device__ __forceinline__ void fused(f32x4 (&acc)[2][2][4][2], const Unit& u, int wr, int wc, int fr, int fq, ldsp lds, int wid, int lane) const {
;     ...
;         for (int bj = 0; bj < 2; ++bj)
; #pragma unroll
;             for (int n = 0; n < 2; ++n) { const int c = colt + bj * HALF + n * 16;
;                 f32x4 gc = *(const f32x4*)(gain + c), sh = (f32x4){0.f, 0.f, 0.f, 0.f};
;                 if (!fin) { gc = gc * (*(const f32x4*)(mb + scoff + c) + 1.0f); sh = *(const f32x4*)(mb + shoff + c); }
; #pragma unroll
;                 for (int ai = 0; ai < 2; ++ai)
; #pragma unroll
;                     for (int m = 0; m < 4; ++m) { const int r = ai * HALF + wr * 64 + m * 16 + fr; const float rs = Sx[r];
;                         const f32x4 y = (acc[ai][bj][m][n] * rs) * gc + sh;
;                         if (fin) *(f32x4*)(xd + (size_t)(rowt + r) * D + c) = y;
;                         else { u32x2 w; w.x = cvt_pk_bf16(y[0], y[1]); w.y = cvt_pk_bf16(y[2], y[3]); *(u32x2*)(H + (size_t)(rowt + r) * D + c) = w; } } }
.LBB0_511:
	ds_read_b32 v72, v96 offset:4736
	s_mov_b64 s[6:7], -1
	s_and_b64 vcc, exec, s[84:85]
	s_waitcnt lgkmcnt(0)
	v_pk_mul_f32 v[70:71], v[70:71], v[72:73] op_sel_hi:[1,0]
	v_pk_mul_f32 v[68:69], v[68:69], v[72:73] op_sel_hi:[1,0]
	v_pk_fma_f32 v[70:71], v[100:101], v[70:71], v[104:105]
	v_pk_fma_f32 v[68:69], v[98:99], v[68:69], v[102:103]
	s_cbranch_vccz .LBB0_513
	v_add_u32_e32 v74, s8, v114
	v_ashrrev_i32_e32 v75, 31, v74
	v_readlane_b32 s4, v254, 35
	v_lshlrev_b64 v[74:75], 11, v[74:75]
	v_readlane_b32 s5, v254, 36
	v_cvt_pk_bf16_f32 v72, v68, v69
	v_cvt_pk_bf16_f32 v73, v70, v71
	s_mov_b64 s[6:7], 0
	s_nop 0
	v_lshl_add_u64 v[74:75], s[4:5], 0, v[74:75]
	v_lshl_add_u64 v[74:75], v[142:143], 1, v[74:75]
	v_mov_b64_e32 v[212:213], v[72:73]
	v_bfe_u32 v194, v196, 4, 1
	v_mov_b32_e32 v195, 0
	v_mul_u32_u24_e32 v194, 24, v194
	v_lshl_add_u64 v[74:75], v[74:75], 0, v[194:195]
	v_permlane16_swap_b32_e32 v210, v212
	v_permlane16_swap_b32_e32 v211, v213
	global_store_dwordx4 v[74:75], v[210:213], off

; __device__ __forceinline__ unsigned cvt_pk_bf16(float lo, float hi) { unsigned r; asm volatile("v_cvt_pk_bf16_f32 %0, %1, %2" : "=v"(r) : "v"(lo), "v"(hi)); return r; }
;     __device__ __forceinline__ void fused(f32x4 (&acc)[2][2][4][2], const Unit& u, int wr, int wc, int fr, int fq, ldsp lds, int wid, int lane) const {
;     ...
;         for (int bj = 0; bj < 2; ++bj)
; #pragma unroll
;             for (int n = 0; n < 2; ++n) { const int c = colt + bj * HALF + n * 16;
;                 f32x4 gc = *(const f32x4*)(gain + c), sh = (f32x4){0.f, 0.f, 0.f, 0.f};
;                 if (!fin) { gc = gc * (*(const f32x4*)(mb + scoff + c) + 1.0f); sh = *(const f32x4*)(mb + shoff + c); }
; #pragma unroll
;                 for (int ai = 0; ai < 2; ++ai)
; #pragma unroll
;                     for (int m = 0; m < 4; ++m) { const int r = ai * HALF + wr * 64 + m * 16 + fr; const float rs = Sx[r];
;                         const f32x4 y = (acc[ai][bj][m][n] * rs) * gc + sh;
;                         if (fin) *(f32x4*)(xd + (size_t)(rowt + r) * D + c) = y;
;                         else { u32x2 w; w.x = cvt_pk_bf16(y[0], y[1]); w.y = cvt_pk_bf16(y[2], y[3]); *(u32x2*)(H + (size_t)(rowt + r) * D + c) = w; } } }
.LBB0_515:
	ds_read_b32 v68, v96 offset:4800
	s_mov_b64 s[6:7], -1
	s_and_b64 vcc, exec, s[84:85]
	s_waitcnt lgkmcnt(0)
	v_pk_mul_f32 v[66:67], v[66:67], v[68:69] op_sel_hi:[1,0]
	v_pk_mul_f32 v[64:65], v[64:65], v[68:69] op_sel_hi:[1,0]
	v_pk_fma_f32 v[66:67], v[100:101], v[66:67], v[104:105]
	v_pk_fma_f32 v[64:65], v[98:99], v[64:65], v[102:103]
	s_cbranch_vccz .LBB0_519
	v_add_u32_e32 v70, s8, v106
	v_ashrrev_i32_e32 v71, 31, v70
	v_readlane_b32 s4, v254, 35
	v_lshlrev_b64 v[70:71], 11, v[70:71]
	v_readlane_b32 s5, v254, 36
	v_cvt_pk_bf16_f32 v68, v64, v65
	v_cvt_pk_bf16_f32 v69, v66, v67
	s_nop 1
	v_lshl_add_u64 v[70:71], s[4:5], 0, v[70:71]
	v_lshl_add_u64 v[70:71], v[142:143], 1, v[70:71]
	v_mov_b64_e32 v[192:193], v[68:69]
	v_bfe_u32 v194, v196, 4, 1
	v_mov_b32_e32 v195, 0
	v_mul_u32_u24_e32 v194, 24, v194
	v_lshl_add_u64 v[70:71], v[70:71], 0, v[194:195]
	v_permlane16_swap_b32_e32 v190, v192
	v_permlane16_swap_b32_e32 v191, v193
	global_store_dwordx4 v[70:71], v[190:193], off
	s_cbranch_execz .LBB0_520

; __device__ __forceinline__ unsigned cvt_pk_bf16(float lo, float hi) { unsigned r; asm volatile("v_cvt_pk_bf16_f32 %0, %1, %2" : "=v"(r) : "v"(lo), "v"(hi)); return r; }
;     __device__ __forceinline__ void fused(f32x4 (&acc)[2][2][4][2], const Unit& u, int wr, int wc, int fr, int fq, ldsp lds, int wid, int lane) const {
;     ...
;         for (int bj = 0; bj < 2; ++bj)
; #pragma unroll
;             for (int n = 0; n < 2; ++n) { const int c = colt + bj * HALF + n * 16;
;                 f32x4 gc = *(const f32x4*)(gain + c), sh = (f32x4){0.f, 0.f, 0.f, 0.f};
;                 if (!fin) { gc = gc * (*(const f32x4*)(mb + scoff + c) + 1.0f); sh = *(const f32x4*)(mb + shoff + c); }
; #pragma unroll
;                 for (int ai = 0; ai < 2; ++ai)
; #pragma unroll
;                     for (int m = 0; m < 4; ++m) { const int r = ai * HALF + wr * 64 + m * 16 + fr; const float rs = Sx[r];
;                         const f32x4 y = (acc[ai][bj][m][n] * rs) * gc + sh;
;                         if (fin) *(f32x4*)(xd + (size_t)(rowt + r) * D + c) = y;
;                         else { u32x2 w; w.x = cvt_pk_bf16(y[0], y[1]); w.y = cvt_pk_bf16(y[2], y[3]); *(u32x2*)(H + (size_t)(rowt + r) * D + c) = w; } } }
.LBB0_522:
	ds_read_b32 v72, v96 offset:4096
	s_mov_b64 s[6:7], -1
	s_and_b64 vcc, exec, s[84:85]
	s_waitcnt lgkmcnt(0)
	v_pk_mul_f32 v[62:63], v[62:63], v[72:73] op_sel_hi:[1,0]
	v_pk_mul_f32 v[60:61], v[60:61], v[72:73] op_sel_hi:[1,0]
	v_pk_fma_f32 v[62:63], v[66:67], v[62:63], v[70:71]
	v_pk_fma_f32 v[60:61], v[64:65], v[60:61], v[68:69]
	s_cbranch_vccz .LBB0_524
	v_add_u32_e32 v74, s8, v148
	v_ashrrev_i32_e32 v75, 31, v74
	v_readlane_b32 s4, v254, 35
	v_lshlrev_b64 v[74:75], 11, v[74:75]
	v_readlane_b32 s5, v254, 36
	v_cvt_pk_bf16_f32 v72, v60, v61
	v_cvt_pk_bf16_f32 v73, v62, v63
	s_mov_b64 s[6:7], 0
	s_nop 0
	v_lshl_add_u64 v[74:75], s[4:5], 0, v[74:75]
	v_lshl_add_u64 v[74:75], v[142:143], 1, v[74:75]
	v_mov_b64_e32 v[238:239], v[72:73]

; __device__ __forceinline__ unsigned cvt_pk_bf16(float lo, float hi) { unsigned r; asm volatile("v_cvt_pk_bf16_f32 %0, %1, %2" : "=v"(r) : "v"(lo), "v"(hi)); return r; }
;     __device__ __forceinline__ void fused(f32x4 (&acc)[2][2][4][2], const Unit& u, int wr, int wc, int fr, int fq, ldsp lds, int wid, int lane) const {
;     ...
;         for (int bj = 0; bj < 2; ++bj)
; #pragma unroll
;             for (int n = 0; n < 2; ++n) { const int c = colt + bj * HALF + n * 16;
;                 f32x4 gc = *(const f32x4*)(gain + c), sh = (f32x4){0.f, 0.f, 0.f, 0.f};
;                 if (!fin) { gc = gc * (*(const f32x4*)(mb + scoff + c) + 1.0f); sh = *(const f32x4*)(mb + shoff + c); }
; #pragma unroll
;                 for (int ai = 0; ai < 2; ++ai)
; #pragma unroll
;                     for (int m = 0; m < 4; ++m) { const int r = ai * HALF + wr * 64 + m * 16 + fr; const float rs = Sx[r];
;                         const f32x4 y = (acc[ai][bj][m][n] * rs) * gc + sh;
;                         if (fin) *(f32x4*)(xd + (size_t)(rowt + r) * D + c) = y;
;                         else { u32x2 w; w.x = cvt_pk_bf16(y[0], y[1]); w.y = cvt_pk_bf16(y[2], y[3]); *(u32x2*)(H + (size_t)(rowt + r) * D + c) = w; } } }
.LBB0_526:
	ds_read_b32 v60, v96 offset:4160
	s_mov_b64 s[6:7], -1
	s_and_b64 vcc, exec, s[84:85]
	s_waitcnt lgkmcnt(0)
	v_pk_mul_f32 v[58:59], v[58:59], v[60:61] op_sel_hi:[1,0]
	v_pk_mul_f32 v[56:57], v[56:57], v[60:61] op_sel_hi:[1,0]
	v_pk_fma_f32 v[58:59], v[66:67], v[58:59], v[70:71]
	v_pk_fma_f32 v[56:57], v[64:65], v[56:57], v[68:69]
	s_cbranch_vccz .LBB0_528
	v_add_u32_e32 v62, s8, v138
	v_ashrrev_i32_e32 v63, 31, v62
	v_readlane_b32 s4, v254, 35
	v_lshlrev_b64 v[62:63], 11, v[62:63]
	v_readlane_b32 s5, v254, 36
	v_cvt_pk_bf16_f32 v60, v56, v57
	v_cvt_pk_bf16_f32 v61, v58, v59
	s_mov_b64 s[6:7], 0
	s_nop 0
	v_lshl_add_u64 v[62:63], s[4:5], 0, v[62:63]
	v_lshl_add_u64 v[62:63], v[142:143], 1, v[62:63]
	v_mov_b64_e32 v[242:243], v[60:61]

; __device__ __forceinline__ unsigned cvt_pk_bf16(float lo, float hi) { unsigned r; asm volatile("v_cvt_pk_bf16_f32 %0, %1, %2" : "=v"(r) : "v"(lo), "v"(hi)); return r; }
;     __device__ __forceinline__ void fused(f32x4 (&acc)[2][2][4][2], const Unit& u, int wr, int wc, int fr, int fq, ldsp lds, int wid, int lane) const {
;     ...
;         for (int bj = 0; bj < 2; ++bj)
; #pragma unroll
;             for (int n = 0; n < 2; ++n) { const int c = colt + bj * HALF + n * 16;
;                 f32x4 gc = *(const f32x4*)(gain + c), sh = (f32x4){0.f, 0.f, 0.f, 0.f};
;                 if (!fin) { gc = gc * (*(const f32x4*)(mb + scoff + c) + 1.0f); sh = *(const f32x4*)(mb + shoff + c); }
; #pragma unroll
;                 for (int ai = 0; ai < 2; ++ai)
; #pragma unroll
;                     for (int m = 0; m < 4; ++m) { const int r = ai * HALF + wr * 64 + m * 16 + fr; const float rs = Sx[r];
;                         const f32x4 y = (acc[ai][bj][m][n] * rs) * gc + sh;
;                         if (fin) *(f32x4*)(xd + (size_t)(rowt + r) * D + c) = y;
;                         else { u32x2 w; w.x = cvt_pk_bf16(y[0], y[1]); w.y = cvt_pk_bf16(y[2], y[3]); *(u32x2*)(H + (size_t)(rowt + r) * D + c) = w; } } }
.LBB0_530:
	ds_read_b32 v56, v96 offset:4224
	s_mov_b64 s[6:7], -1
	s_and_b64 vcc, exec, s[84:85]
	s_waitcnt lgkmcnt(0)
	v_pk_mul_f32 v[54:55], v[54:55], v[56:57] op_sel_hi:[1,0]
	v_pk_mul_f32 v[52:53], v[52:53], v[56:57] op_sel_hi:[1,0]
	v_pk_fma_f32 v[54:55], v[66:67], v[54:55], v[70:71]
	v_pk_fma_f32 v[52:53], v[64:65], v[52:53], v[68:69]
	s_cbranch_vccz .LBB0_532
	v_add_u32_e32 v58, s8, v134
	v_ashrrev_i32_e32 v59, 31, v58
	v_readlane_b32 s4, v254, 35
	v_lshlrev_b64 v[58:59], 11, v[58:59]
	v_readlane_b32 s5, v254, 36
	v_cvt_pk_bf16_f32 v56, v52, v53
	v_cvt_pk_bf16_f32 v57, v54, v55
	s_mov_b64 s[6:7], 0
	s_nop 0
	v_lshl_add_u64 v[58:59], s[4:5], 0, v[58:59]
	v_lshl_add_u64 v[58:59], v[142:143], 1, v[58:59]
	v_mov_b64_e32 v[246:247], v[56:57]

; __device__ __forceinline__ unsigned cvt_pk_bf16(float lo, float hi) { unsigned r; asm volatile("v_cvt_pk_bf16_f32 %0, %1, %2" : "=v"(r) : "v"(lo), "v"(hi)); return r; }
;     __device__ __forceinline__ void fused(f32x4 (&acc)[2][2][4][2], const Unit& u, int wr, int wc, int fr, int fq, ldsp lds, int wid, int lane) const {
;     ...
;         for (int bj = 0; bj < 2; ++bj)
; #pragma unroll
;             for (int n = 0; n < 2; ++n) { const int c = colt + bj * HALF + n * 16;
;                 f32x4 gc = *(const f32x4*)(gain + c), sh = (f32x4){0.f, 0.f, 0.f, 0.f};
;                 if (!fin) { gc = gc * (*(const f32x4*)(mb + scoff + c) + 1.0f); sh = *(const f32x4*)(mb + shoff + c); }
; #pragma unroll
;                 for (int ai = 0; ai < 2; ++ai)
; #pragma unroll
;                     for (int m = 0; m < 4; ++m) { const int r = ai * HALF + wr * 64 + m * 16 + fr; const float rs = Sx[r];
;                         const f32x4 y = (acc[ai][bj][m][n] * rs) * gc + sh;
;                         if (fin) *(f32x4*)(xd + (size_t)(rowt + r) * D + c) = y;
;                         else { u32x2 w; w.x = cvt_pk_bf16(y[0], y[1]); w.y = cvt_pk_bf16(y[2], y[3]); *(u32x2*)(H + (size_t)(rowt + r) * D + c) = w; } } }
.LBB0_534:
	ds_read_b32 v52, v96 offset:4288
	s_mov_b64 s[6:7], -1
	s_and_b64 vcc, exec, s[84:85]
	s_waitcnt lgkmcnt(0)
	v_pk_mul_f32 v[50:51], v[50:51], v[52:53] op_sel_hi:[1,0]
	v_pk_mul_f32 v[48:49], v[48:49], v[52:53] op_sel_hi:[1,0]
	v_pk_fma_f32 v[50:51], v[66:67], v[50:51], v[70:71]
	v_pk_fma_f32 v[48:49], v[64:65], v[48:49], v[68:69]
	s_cbranch_vccz .LBB0_536
	v_add_u32_e32 v54, s8, v130
	v_ashrrev_i32_e32 v55, 31, v54
	v_readlane_b32 s4, v254, 35
	v_lshlrev_b64 v[54:55], 11, v[54:55]
	v_readlane_b32 s5, v254, 36
	v_cvt_pk_bf16_f32 v52, v48, v49
	v_cvt_pk_bf16_f32 v53, v50, v51
	s_mov_b64 s[6:7], 0
	s_nop 0
	v_lshl_add_u64 v[54:55], s[4:5], 0, v[54:55]
	v_lshl_add_u64 v[54:55], v[142:143], 1, v[54:55]
	v_mov_b64_e32 v[250:251], v[52:53]

; __device__ __forceinline__ unsigned cvt_pk_bf16(float lo, float hi) { unsigned r; asm volatile("v_cvt_pk_bf16_f32 %0, %1, %2" : "=v"(r) : "v"(lo), "v"(hi)); return r; }
;     __device__ __forceinline__ void fused(f32x4 (&acc)[2][2][4][2], const Unit& u, int wr, int wc, int fr, int fq, ldsp lds, int wid, int lane) const {
;     ...
;         for (int bj = 0; bj < 2; ++bj)
; #pragma unroll
;             for (int n = 0; n < 2; ++n) { const int c = colt + bj * HALF + n * 16;
;                 f32x4 gc = *(const f32x4*)(gain + c), sh = (f32x4){0.f, 0.f, 0.f, 0.f};
;                 if (!fin) { gc = gc * (*(const f32x4*)(mb + scoff + c) + 1.0f); sh = *(const f32x4*)(mb + shoff + c); }
; #pragma unroll
;                 for (int ai = 0; ai < 2; ++ai)
; #pragma unroll
;                     for (int m = 0; m < 4; ++m) { const int r = ai * HALF + wr * 64 + m * 16 + fr; const float rs = Sx[r];
;                         const f32x4 y = (acc[ai][bj][m][n] * rs) * gc + sh;
;                         if (fin) *(f32x4*)(xd + (size_t)(rowt + r) * D + c) = y;
;                         else { u32x2 w; w.x = cvt_pk_bf16(y[0], y[1]); w.y = cvt_pk_bf16(y[2], y[3]); *(u32x2*)(H + (size_t)(rowt + r) * D + c) = w; } } }
.LBB0_538:
	ds_read_b32 v48, v96 offset:4608
	s_mov_b64 s[6:7], -1
	s_and_b64 vcc, exec, s[84:85]
	s_waitcnt lgkmcnt(0)
	v_pk_mul_f32 v[46:47], v[46:47], v[48:49] op_sel_hi:[1,0]
	v_pk_mul_f32 v[44:45], v[44:45], v[48:49] op_sel_hi:[1,0]
	v_pk_fma_f32 v[46:47], v[66:67], v[46:47], v[70:71]
	v_pk_fma_f32 v[44:45], v[64:65], v[44:45], v[68:69]
	s_cbranch_vccz .LBB0_540
	v_add_u32_e32 v50, s8, v126
	v_ashrrev_i32_e32 v51, 31, v50
	v_readlane_b32 s4, v254, 35
	v_lshlrev_b64 v[50:51], 11, v[50:51]
	v_readlane_b32 s5, v254, 36
	v_cvt_pk_bf16_f32 v48, v44, v45
	v_cvt_pk_bf16_f32 v49, v46, v47
	s_mov_b64 s[6:7], 0
	s_nop 0
	v_lshl_add_u64 v[50:51], s[4:5], 0, v[50:51]
	v_lshl_add_u64 v[50:51], v[142:143], 1, v[50:51]
	v_mov_b64_e32 v[202:203], v[48:49]

; __device__ __forceinline__ unsigned cvt_pk_bf16(float lo, float hi) { unsigned r; asm volatile("v_cvt_pk_bf16_f32 %0, %1, %2" : "=v"(r) : "v"(lo), "v"(hi)); return r; }
;     __device__ __forceinline__ void fused(f32x4 (&acc)[2][2][4][2], const Unit& u, int wr, int wc, int fr, int fq, ldsp lds, int wid, int lane) const {
;     ...
;         for (int bj = 0; bj < 2; ++bj)
; #pragma unroll
;             for (int n = 0; n < 2; ++n) { const int c = colt + bj * HALF + n * 16;
;                 f32x4 gc = *(const f32x4*)(gain + c), sh = (f32x4){0.f, 0.f, 0.f, 0.f};
;                 if (!fin) { gc = gc * (*(const f32x4*)(mb + scoff + c) + 1.0f); sh = *(const f32x4*)(mb + shoff + c); }
; #pragma unroll
;                 for (int ai = 0; ai < 2; ++ai)
; #pragma unroll
;                     for (int m = 0; m < 4; ++m) { const int r = ai * HALF + wr * 64 + m * 16 + fr; const float rs = Sx[r];
;                         const f32x4 y = (acc[ai][bj][m][n] * rs) * gc + sh;
;                         if (fin) *(f32x4*)(xd + (size_t)(rowt + r) * D + c) = y;
;                         else { u32x2 w; w.x = cvt_pk_bf16(y[0], y[1]); w.y = cvt_pk_bf16(y[2], y[3]); *(u32x2*)(H + (size_t)(rowt + r) * D + c) = w; } } }
.LBB0_542:
	ds_read_b32 v44, v96 offset:4672
	s_mov_b64 s[6:7], -1
	s_and_b64 vcc, exec, s[84:85]
	s_waitcnt lgkmcnt(0)
	v_pk_mul_f32 v[42:43], v[42:43], v[44:45] op_sel_hi:[1,0]
	v_pk_mul_f32 v[40:41], v[40:41], v[44:45] op_sel_hi:[1,0]
	v_pk_fma_f32 v[42:43], v[66:67], v[42:43], v[70:71]
	v_pk_fma_f32 v[40:41], v[64:65], v[40:41], v[68:69]
	s_cbranch_vccz .LBB0_544
	v_add_u32_e32 v46, s8, v118
	v_ashrrev_i32_e32 v47, 31, v46
	v_readlane_b32 s4, v254, 35
	v_lshlrev_b64 v[46:47], 11, v[46:47]
	v_readlane_b32 s5, v254, 36
	v_cvt_pk_bf16_f32 v44, v40, v41
	v_cvt_pk_bf16_f32 v45, v42, v43
	s_mov_b64 s[6:7], 0
	s_nop 0
	v_lshl_add_u64 v[46:47], s[4:5], 0, v[46:47]
	v_lshl_add_u64 v[46:47], v[142:143], 1, v[46:47]
	v_mov_b64_e32 v[206:207], v[44:45]

; __device__ __forceinline__ unsigned cvt_pk_bf16(float lo, float hi) { unsigned r; asm volatile("v_cvt_pk_bf16_f32 %0, %1, %2" : "=v"(r) : "v"(lo), "v"(hi)); return r; }
;     __device__ __forceinline__ void fused(f32x4 (&acc)[2][2][4][2], const Unit& u, int wr, int wc, int fr, int fq, ldsp lds, int wid, int lane) const {
;     ...
;         for (int bj = 0; bj < 2; ++bj)
; #pragma unroll
;             for (int n = 0; n < 2; ++n) { const int c = colt + bj * HALF + n * 16;
;                 f32x4 gc = *(const f32x4*)(gain + c), sh = (f32x4){0.f, 0.f, 0.f, 0.f};
;                 if (!fin) { gc = gc * (*(const f32x4*)(mb + scoff + c) + 1.0f); sh = *(const f32x4*)(mb + shoff + c); }
; #pragma unroll
;                 for (int ai = 0; ai < 2; ++ai)
; #pragma unroll
;                     for (int m = 0; m < 4; ++m) { const int r = ai * HALF + wr * 64 + m * 16 + fr; const float rs = Sx[r];
;                         const f32x4 y = (acc[ai][bj][m][n] * rs) * gc + sh;
;                         if (fin) *(f32x4*)(xd + (size_t)(rowt + r) * D + c) = y;
;                         else { u32x2 w; w.x = cvt_pk_bf16(y[0], y[1]); w.y = cvt_pk_bf16(y[2], y[3]); *(u32x2*)(H + (size_t)(rowt + r) * D + c) = w; } } }
.LBB0_546:
	ds_read_b32 v40, v96 offset:4736
	s_mov_b64 s[6:7], -1
	s_and_b64 vcc, exec, s[84:85]
	s_waitcnt lgkmcnt(0)
	v_pk_mul_f32 v[38:39], v[38:39], v[40:41] op_sel_hi:[1,0]
	v_pk_mul_f32 v[36:37], v[36:37], v[40:41] op_sel_hi:[1,0]
	v_pk_fma_f32 v[38:39], v[66:67], v[38:39], v[70:71]
	v_pk_fma_f32 v[36:37], v[64:65], v[36:37], v[68:69]
	s_cbranch_vccz .LBB0_548
	v_add_u32_e32 v42, s8, v114
	v_ashrrev_i32_e32 v43, 31, v42
	v_readlane_b32 s4, v254, 35
	v_lshlrev_b64 v[42:43], 11, v[42:43]
	v_readlane_b32 s5, v254, 36
	v_cvt_pk_bf16_f32 v40, v36, v37
	v_cvt_pk_bf16_f32 v41, v38, v39
	s_mov_b64 s[6:7], 0
	s_nop 0
	v_lshl_add_u64 v[42:43], s[4:5], 0, v[42:43]
	v_lshl_add_u64 v[42:43], v[142:143], 1, v[42:43]
	v_mov_b64_e32 v[210:211], v[40:41]

; __device__ __forceinline__ unsigned cvt_pk_bf16(float lo, float hi) { unsigned r; asm volatile("v_cvt_pk_bf16_f32 %0, %1, %2" : "=v"(r) : "v"(lo), "v"(hi)); return r; }
;     __device__ __forceinline__ void fused(f32x4 (&acc)[2][2][4][2], const Unit& u, int wr, int wc, int fr, int fq, ldsp lds, int wid, int lane) const {
;     ...
;         for (int bj = 0; bj < 2; ++bj)
; #pragma unroll
;             for (int n = 0; n < 2; ++n) { const int c = colt + bj * HALF + n * 16;
;                 f32x4 gc = *(const f32x4*)(gain + c), sh = (f32x4){0.f, 0.f, 0.f, 0.f};
;                 if (!fin) { gc = gc * (*(const f32x4*)(mb + scoff + c) + 1.0f); sh = *(const f32x4*)(mb + shoff + c); }
; #pragma unroll
;                 for (int ai = 0; ai < 2; ++ai)
; #pragma unroll
;                     for (int m = 0; m < 4; ++m) { const int r = ai * HALF + wr * 64 + m * 16 + fr; const float rs = Sx[r];
;                         const f32x4 y = (acc[ai][bj][m][n] * rs) * gc + sh;
;                         if (fin) *(f32x4*)(xd + (size_t)(rowt + r) * D + c) = y;
;                         else { u32x2 w; w.x = cvt_pk_bf16(y[0], y[1]); w.y = cvt_pk_bf16(y[2], y[3]); *(u32x2*)(H + (size_t)(rowt + r) * D + c) = w; } } }
.LBB0_550:
	ds_read_b32 v36, v96 offset:4800
	s_mov_b64 s[6:7], -1
	s_and_b64 vcc, exec, s[84:85]
	s_waitcnt lgkmcnt(0)
	v_pk_mul_f32 v[34:35], v[34:35], v[36:37] op_sel_hi:[1,0]
	v_pk_mul_f32 v[32:33], v[32:33], v[36:37] op_sel_hi:[1,0]
	v_pk_fma_f32 v[34:35], v[66:67], v[34:35], v[70:71]
	v_pk_fma_f32 v[32:33], v[64:65], v[32:33], v[68:69]
	s_cbranch_vccz .LBB0_554
	v_add_u32_e32 v38, s8, v106
	v_ashrrev_i32_e32 v39, 31, v38
	v_readlane_b32 s4, v254, 35
	v_lshlrev_b64 v[38:39], 11, v[38:39]
	v_readlane_b32 s5, v254, 36
	v_cvt_pk_bf16_f32 v36, v32, v33
	v_cvt_pk_bf16_f32 v37, v34, v35
	s_nop 1
	v_lshl_add_u64 v[38:39], s[4:5], 0, v[38:39]
	v_lshl_add_u64 v[38:39], v[142:143], 1, v[38:39]
	v_mov_b64_e32 v[190:191], v[36:37]
	s_cbranch_execz .LBB0_555

; __device__ __forceinline__ unsigned cvt_pk_bf16(float lo, float hi) { unsigned r; asm volatile("v_cvt_pk_bf16_f32 %0, %1, %2" : "=v"(r) : "v"(lo), "v"(hi)); return r; }
;     __device__ __forceinline__ void fused(f32x4 (&acc)[2][2][4][2], const Unit& u, int wr, int wc, int fr, int fq, ldsp lds, int wid, int lane) const {
;     ...
;         const int colt = u.pn * BM + wc * 32 + 4 * fq;
;         const float* mb = modn + (size_t)b * NMOD;
; #pragma unroll
;         for (int bj = 0; bj < 2; ++bj)
; #pragma unroll
;             for (int n = 0; n < 2; ++n) { const int c = colt + bj * HALF + n * 16;
;                 f32x4 gc = *(const f32x4*)(gain + c), sh = (f32x4){0.f, 0.f, 0.f, 0.f};
;                 if (!fin) { gc = gc * (*(const f32x4*)(mb + scoff + c) + 1.0f); sh = *(const f32x4*)(mb + shoff + c); }
; #pragma unroll
;                 for (int ai = 0; ai < 2; ++ai)
; #pragma unroll
;                     for (int m = 0; m < 4; ++m) { const int r = ai * HALF + wr * 64 + m * 16 + fr; const float rs = Sx[r];
;                         const f32x4 y = (acc[ai][bj][m][n] * rs) * gc + sh;
;                         if (fin) *(f32x4*)(xd + (size_t)(rowt + r) * D + c) = y;
;                         else { u32x2 w; w.x = cvt_pk_bf16(y[0], y[1]); w.y = cvt_pk_bf16(y[2], y[3]); *(u32x2*)(H + (size_t)(rowt + r) * D + c) = w; } } }
.LBB0_557:
	ds_read_b32 v40, v96 offset:4096
	s_mov_b64 s[6:7], -1
	s_and_b64 vcc, exec, s[84:85]
	s_waitcnt lgkmcnt(0)
	v_pk_mul_f32 v[30:31], v[30:31], v[40:41] op_sel_hi:[1,0]
	v_pk_mul_f32 v[28:29], v[28:29], v[40:41] op_sel_hi:[1,0]
	v_pk_fma_f32 v[30:31], v[34:35], v[30:31], v[38:39]
	v_pk_fma_f32 v[28:29], v[32:33], v[28:29], v[36:37]
	s_cbranch_vccz .LBB0_559
	v_add_u32_e32 v42, s8, v148
	v_ashrrev_i32_e32 v43, 31, v42
	v_readlane_b32 s0, v254, 35
	v_lshlrev_b64 v[42:43], 11, v[42:43]
	v_readlane_b32 s1, v254, 36
	v_cvt_pk_bf16_f32 v40, v28, v29
	v_cvt_pk_bf16_f32 v41, v30, v31
	s_mov_b64 s[6:7], 0
	s_nop 0
	v_lshl_add_u64 v[42:43], s[0:1], 0, v[42:43]
	v_lshl_add_u64 v[42:43], v[142:143], 1, v[42:43]
	v_mov_b64_e32 v[240:241], v[40:41]
	v_bfe_u32 v194, v196, 4, 1
	v_mov_b32_e32 v195, 0
	v_mul_u32_u24_e32 v194, 24, v194
	v_lshl_add_u64 v[42:43], v[42:43], 0, v[194:195]
	v_permlane16_swap_b32_e32 v238, v240
	v_permlane16_swap_b32_e32 v239, v241
	global_store_dwordx4 v[42:43], v[238:241], off offset:256

; __device__ __forceinline__ unsigned cvt_pk_bf16(float lo, float hi) { unsigned r; asm volatile("v_cvt_pk_bf16_f32 %0, %1, %2" : "=v"(r) : "v"(lo), "v"(hi)); return r; }
;     __device__ __forceinline__ void fused(f32x4 (&acc)[2][2][4][2], const Unit& u, int wr, int wc, int fr, int fq, ldsp lds, int wid, int lane) const {
;     ...
;         const int colt = u.pn * BM + wc * 32 + 4 * fq;
;         const float* mb = modn + (size_t)b * NMOD;
; #pragma unroll
;         for (int bj = 0; bj < 2; ++bj)
; #pragma unroll
;             for (int n = 0; n < 2; ++n) { const int c = colt + bj * HALF + n * 16;
;                 f32x4 gc = *(const f32x4*)(gain + c), sh = (f32x4){0.f, 0.f, 0.f, 0.f};
;                 if (!fin) { gc = gc * (*(const f32x4*)(mb + scoff + c) + 1.0f); sh = *(const f32x4*)(mb + shoff + c); }
; #pragma unroll
;                 for (int ai = 0; ai < 2; ++ai)
; #pragma unroll
;                     for (int m = 0; m < 4; ++m) { const int r = ai * HALF + wr * 64 + m * 16 + fr; const float rs = Sx[r];
;                         const f32x4 y = (acc[ai][bj][m][n] * rs) * gc + sh;
;                         if (fin) *(f32x4*)(xd + (size_t)(rowt + r) * D + c) = y;
;                         else { u32x2 w; w.x = cvt_pk_bf16(y[0], y[1]); w.y = cvt_pk_bf16(y[2], y[3]); *(u32x2*)(H + (size_t)(rowt + r) * D + c) = w; } } }
.LBB0_561:
	ds_read_b32 v28, v96 offset:4160
	s_mov_b64 s[6:7], -1
	s_and_b64 vcc, exec, s[84:85]
	s_waitcnt lgkmcnt(0)
	v_pk_mul_f32 v[26:27], v[26:27], v[28:29] op_sel_hi:[1,0]
	v_pk_mul_f32 v[24:25], v[24:25], v[28:29] op_sel_hi:[1,0]
	v_pk_fma_f32 v[26:27], v[34:35], v[26:27], v[38:39]
	v_pk_fma_f32 v[24:25], v[32:33], v[24:25], v[36:37]
	s_cbranch_vccz .LBB0_563
	v_add_u32_e32 v30, s8, v138
	v_ashrrev_i32_e32 v31, 31, v30
	v_readlane_b32 s0, v254, 35
	v_lshlrev_b64 v[30:31], 11, v[30:31]
	v_readlane_b32 s1, v254, 36
	v_cvt_pk_bf16_f32 v28, v24, v25
	v_cvt_pk_bf16_f32 v29, v26, v27
	s_mov_b64 s[6:7], 0
	s_nop 0
	v_lshl_add_u64 v[30:31], s[0:1], 0, v[30:31]
	v_lshl_add_u64 v[30:31], v[142:143], 1, v[30:31]
	v_mov_b64_e32 v[244:245], v[28:29]
	v_bfe_u32 v194, v196, 4, 1
	v_mov_b32_e32 v195, 0
	v_mul_u32_u24_e32 v194, 24, v194
	v_lshl_add_u64 v[30:31], v[30:31], 0, v[194:195]
	v_permlane16_swap_b32_e32 v242, v244
	v_permlane16_swap_b32_e32 v243, v245
	global_store_dwordx4 v[30:31], v[242:245], off offset:256

; __device__ __forceinline__ unsigned cvt_pk_bf16(float lo, float hi) { unsigned r; asm volatile("v_cvt_pk_bf16_f32 %0, %1, %2" : "=v"(r) : "v"(lo), "v"(hi)); return r; }
;     __device__ __forceinline__ void fused(f32x4 (&acc)[2][2][4][2], const Unit& u, int wr, int wc, int fr, int fq, ldsp lds, int wid, int lane) const {
;     ...
;         const int colt = u.pn * BM + wc * 32 + 4 * fq;
;         const float* mb = modn + (size_t)b * NMOD;
; #pragma unroll
;         for (int bj = 0; bj < 2; ++bj)
; #pragma unroll
;             for (int n = 0; n < 2; ++n) { const int c = colt + bj * HALF + n * 16;
;                 f32x4 gc = *(const f32x4*)(gain + c), sh = (f32x4){0.f, 0.f, 0.f, 0.f};
;                 if (!fin) { gc = gc * (*(const f32x4*)(mb + scoff + c) + 1.0f); sh = *(const f32x4*)(mb + shoff + c); }
; #pragma unroll
;                 for (int ai = 0; ai < 2; ++ai)
; #pragma unroll
;                     for (int m = 0; m < 4; ++m) { const int r = ai * HALF + wr * 64 + m * 16 + fr; const float rs = Sx[r];
;                         const f32x4 y = (acc[ai][bj][m][n] * rs) * gc + sh;
;                         if (fin) *(f32x4*)(xd + (size_t)(rowt + r) * D + c) = y;
;                         else { u32x2 w; w.x = cvt_pk_bf16(y[0], y[1]); w.y = cvt_pk_bf16(y[2], y[3]); *(u32x2*)(H + (size_t)(rowt + r) * D + c) = w; } } }
.LBB0_565:
	ds_read_b32 v24, v96 offset:4224
	s_mov_b64 s[6:7], -1
	s_and_b64 vcc, exec, s[84:85]
	s_waitcnt lgkmcnt(0)
	v_pk_mul_f32 v[22:23], v[22:23], v[24:25] op_sel_hi:[1,0]
	v_pk_mul_f32 v[20:21], v[20:21], v[24:25] op_sel_hi:[1,0]
	v_pk_fma_f32 v[22:23], v[34:35], v[22:23], v[38:39]
	v_pk_fma_f32 v[20:21], v[32:33], v[20:21], v[36:37]
	s_cbranch_vccz .LBB0_567
	v_add_u32_e32 v26, s8, v134
	v_ashrrev_i32_e32 v27, 31, v26
	v_readlane_b32 s0, v254, 35
	v_lshlrev_b64 v[26:27], 11, v[26:27]
	v_readlane_b32 s1, v254, 36
	v_cvt_pk_bf16_f32 v24, v20, v21
	v_cvt_pk_bf16_f32 v25, v22, v23
	s_mov_b64 s[6:7], 0
	s_nop 0
	v_lshl_add_u64 v[26:27], s[0:1], 0, v[26:27]
	v_lshl_add_u64 v[26:27], v[142:143], 1, v[26:27]
	v_mov_b64_e32 v[248:249], v[24:25]
	v_bfe_u32 v194, v196, 4, 1
	v_mov_b32_e32 v195, 0
	v_mul_u32_u24_e32 v194, 24, v194
	v_lshl_add_u64 v[26:27], v[26:27], 0, v[194:195]
	v_permlane16_swap_b32_e32 v246, v248
	v_permlane16_swap_b32_e32 v247, v249
	global_store_dwordx4 v[26:27], v[246:249], off offset:256

; __device__ __forceinline__ unsigned cvt_pk_bf16(float lo, float hi) { unsigned r; asm volatile("v_cvt_pk_bf16_f32 %0, %1, %2" : "=v"(r) : "v"(lo), "v"(hi)); return r; }
;     __device__ __forceinline__ void fused(f32x4 (&acc)[2][2][4][2], const Unit& u, int wr, int wc, int fr, int fq, ldsp lds, int wid, int lane) const {
;     ...
;         const int colt = u.pn * BM + wc * 32 + 4 * fq;
;         const float* mb = modn + (size_t)b * NMOD;
; #pragma unroll
;         for (int bj = 0; bj < 2; ++bj)
; #pragma unroll
;             for (int n = 0; n < 2; ++n) { const int c = colt + bj * HALF + n * 16;
;                 f32x4 gc = *(const f32x4*)(gain + c), sh = (f32x4){0.f, 0.f, 0.f, 0.f};
;                 if (!fin) { gc = gc * (*(const f32x4*)(mb + scoff + c) + 1.0f); sh = *(const f32x4*)(mb + shoff + c); }
; #pragma unroll
;                 for (int ai = 0; ai < 2; ++ai)
; #pragma unroll
;                     for (int m = 0; m < 4; ++m) { const int r = ai * HALF + wr * 64 + m * 16 + fr; const float rs = Sx[r];
;                         const f32x4 y = (acc[ai][bj][m][n] * rs) * gc + sh;
;                         if (fin) *(f32x4*)(xd + (size_t)(rowt + r) * D + c) = y;
;                         else { u32x2 w; w.x = cvt_pk_bf16(y[0], y[1]); w.y = cvt_pk_bf16(y[2], y[3]); *(u32x2*)(H + (size_t)(rowt + r) * D + c) = w; } } }
.LBB0_569:
	ds_read_b32 v20, v96 offset:4288
	s_mov_b64 s[6:7], -1
	s_and_b64 vcc, exec, s[84:85]
	s_waitcnt lgkmcnt(0)
	v_pk_mul_f32 v[18:19], v[18:19], v[20:21] op_sel_hi:[1,0]
	v_pk_mul_f32 v[16:17], v[16:17], v[20:21] op_sel_hi:[1,0]
	v_pk_fma_f32 v[18:19], v[34:35], v[18:19], v[38:39]
	v_pk_fma_f32 v[16:17], v[32:33], v[16:17], v[36:37]
	s_cbranch_vccz .LBB0_571
	v_add_u32_e32 v22, s8, v130
	v_ashrrev_i32_e32 v23, 31, v22
	v_readlane_b32 s0, v254, 35
	v_lshlrev_b64 v[22:23], 11, v[22:23]
	v_readlane_b32 s1, v254, 36
	v_cvt_pk_bf16_f32 v20, v16, v17
	v_cvt_pk_bf16_f32 v21, v18, v19
	s_mov_b64 s[6:7], 0
	s_nop 0
	v_lshl_add_u64 v[22:23], s[0:1], 0, v[22:23]
	v_lshl_add_u64 v[22:23], v[142:143], 1, v[22:23]
	v_mov_b64_e32 v[252:253], v[20:21]
	v_bfe_u32 v194, v196, 4, 1
	v_mov_b32_e32 v195, 0
	v_mul_u32_u24_e32 v194, 24, v194
	v_lshl_add_u64 v[22:23], v[22:23], 0, v[194:195]
	v_permlane16_swap_b32_e32 v250, v252
	v_permlane16_swap_b32_e32 v251, v253
	global_store_dwordx4 v[22:23], v[250:253], off offset:256

; __device__ __forceinline__ unsigned cvt_pk_bf16(float lo, float hi) { unsigned r; asm volatile("v_cvt_pk_bf16_f32 %0, %1, %2" : "=v"(r) : "v"(lo), "v"(hi)); return r; }
;     __device__ __forceinline__ void fused(f32x4 (&acc)[2][2][4][2], const Unit& u, int wr, int wc, int fr, int fq, ldsp lds, int wid, int lane) const {
;     ...
;         const int colt = u.pn * BM + wc * 32 + 4 * fq;
;         const float* mb = modn + (size_t)b * NMOD;
; #pragma unroll
;         for (int bj = 0; bj < 2; ++bj)
; #pragma unroll
;             for (int n = 0; n < 2; ++n) { const int c = colt + bj * HALF + n * 16;
;                 f32x4 gc = *(const f32x4*)(gain + c), sh = (f32x4){0.f, 0.f, 0.f, 0.f};
;                 if (!fin) { gc = gc * (*(const f32x4*)(mb + scoff + c) + 1.0f); sh = *(const f32x4*)(mb + shoff + c); }
; #pragma unroll
;                 for (int ai = 0; ai < 2; ++ai)
; #pragma unroll
;                     for (int m = 0; m < 4; ++m) { const int r = ai * HALF + wr * 64 + m * 16 + fr; const float rs = Sx[r];
;                         const f32x4 y = (acc[ai][bj][m][n] * rs) * gc + sh;
;                         if (fin) *(f32x4*)(xd + (size_t)(rowt + r) * D + c) = y;
;                         else { u32x2 w; w.x = cvt_pk_bf16(y[0], y[1]); w.y = cvt_pk_bf16(y[2], y[3]); *(u32x2*)(H + (size_t)(rowt + r) * D + c) = w; } } }
.LBB0_573:
	ds_read_b32 v16, v96 offset:4608
	s_mov_b64 s[6:7], -1
	s_and_b64 vcc, exec, s[84:85]
	s_waitcnt lgkmcnt(0)
	v_pk_mul_f32 v[14:15], v[14:15], v[16:17] op_sel_hi:[1,0]
	v_pk_mul_f32 v[12:13], v[12:13], v[16:17] op_sel_hi:[1,0]
	v_pk_fma_f32 v[14:15], v[34:35], v[14:15], v[38:39]
	v_pk_fma_f32 v[12:13], v[32:33], v[12:13], v[36:37]
	s_cbranch_vccz .LBB0_575
	v_add_u32_e32 v18, s8, v126
	v_ashrrev_i32_e32 v19, 31, v18
	v_readlane_b32 s0, v254, 35
	v_lshlrev_b64 v[18:19], 11, v[18:19]
	v_readlane_b32 s1, v254, 36
	v_cvt_pk_bf16_f32 v16, v12, v13
	v_cvt_pk_bf16_f32 v17, v14, v15
	s_mov_b64 s[6:7], 0
	s_nop 0
	v_lshl_add_u64 v[18:19], s[0:1], 0, v[18:19]
	v_lshl_add_u64 v[18:19], v[142:143], 1, v[18:19]
	v_mov_b64_e32 v[204:205], v[16:17]
	v_bfe_u32 v194, v196, 4, 1
	v_mov_b32_e32 v195, 0
	v_mul_u32_u24_e32 v194, 24, v194
	v_lshl_add_u64 v[18:19], v[18:19], 0, v[194:195]
	v_permlane16_swap_b32_e32 v202, v204
	v_permlane16_swap_b32_e32 v203, v205
	global_store_dwordx4 v[18:19], v[202:205], off offset:256

; __device__ __forceinline__ unsigned cvt_pk_bf16(float lo, float hi) { unsigned r; asm volatile("v_cvt_pk_bf16_f32 %0, %1, %2" : "=v"(r) : "v"(lo), "v"(hi)); return r; }
;     __device__ __forceinline__ void fused(f32x4 (&acc)[2][2][4][2], const Unit& u, int wr, int wc, int fr, int fq, ldsp lds, int wid, int lane) const {
;     ...
;         const int colt = u.pn * BM + wc * 32 + 4 * fq;
;         const float* mb = modn + (size_t)b * NMOD;
; #pragma unroll
;         for (int bj = 0; bj < 2; ++bj)
; #pragma unroll
;             for (int n = 0; n < 2; ++n) { const int c = colt + bj * HALF + n * 16;
;                 f32x4 gc = *(const f32x4*)(gain + c), sh = (f32x4){0.f, 0.f, 0.f, 0.f};
;                 if (!fin) { gc = gc * (*(const f32x4*)(mb + scoff + c) + 1.0f); sh = *(const f32x4*)(mb + shoff + c); }
; #pragma unroll
;                 for (int ai = 0; ai < 2; ++ai)
; #pragma unroll
;                     for (int m = 0; m < 4; ++m) { const int r = ai * HALF + wr * 64 + m * 16 + fr; const float rs = Sx[r];
;                         const f32x4 y = (acc[ai][bj][m][n] * rs) * gc + sh;
;                         if (fin) *(f32x4*)(xd + (size_t)(rowt + r) * D + c) = y;
;                         else { u32x2 w; w.x = cvt_pk_bf16(y[0], y[1]); w.y = cvt_pk_bf16(y[2], y[3]); *(u32x2*)(H + (size_t)(rowt + r) * D + c) = w; } } }
.LBB0_577:
	ds_read_b32 v12, v96 offset:4672
	s_mov_b64 s[6:7], -1
	s_and_b64 vcc, exec, s[84:85]
	s_waitcnt lgkmcnt(0)
	v_pk_mul_f32 v[10:11], v[10:11], v[12:13] op_sel_hi:[1,0]
	v_pk_mul_f32 v[8:9], v[8:9], v[12:13] op_sel_hi:[1,0]
	v_pk_fma_f32 v[10:11], v[34:35], v[10:11], v[38:39]
	v_pk_fma_f32 v[8:9], v[32:33], v[8:9], v[36:37]
	s_cbranch_vccz .LBB0_579
	v_add_u32_e32 v14, s8, v118
	v_ashrrev_i32_e32 v15, 31, v14
	v_readlane_b32 s0, v254, 35
	v_lshlrev_b64 v[14:15], 11, v[14:15]
	v_readlane_b32 s1, v254, 36
	v_cvt_pk_bf16_f32 v12, v8, v9
	v_cvt_pk_bf16_f32 v13, v10, v11
	s_mov_b64 s[6:7], 0
	s_nop 0
	v_lshl_add_u64 v[14:15], s[0:1], 0, v[14:15]
	v_lshl_add_u64 v[14:15], v[142:143], 1, v[14:15]
	v_mov_b64_e32 v[208:209], v[12:13]
	v_bfe_u32 v194, v196, 4, 1
	v_mov_b32_e32 v195, 0
	v_mul_u32_u24_e32 v194, 24, v194
	v_lshl_add_u64 v[14:15], v[14:15], 0, v[194:195]
	v_permlane16_swap_b32_e32 v206, v208
	v_permlane16_swap_b32_e32 v207, v209
	global_store_dwordx4 v[14:15], v[206:209], off offset:256

; __device__ __forceinline__ unsigned cvt_pk_bf16(float lo, float hi) { unsigned r; asm volatile("v_cvt_pk_bf16_f32 %0, %1, %2" : "=v"(r) : "v"(lo), "v"(hi)); return r; }
;     __device__ __forceinline__ void fused(f32x4 (&acc)[2][2][4][2], const Unit& u, int wr, int wc, int fr, int fq, ldsp lds, int wid, int lane) const {
;     ...
;         const int colt = u.pn * BM + wc * 32 + 4 * fq;
;         const float* mb = modn + (size_t)b * NMOD;
; #pragma unroll
;         for (int bj = 0; bj < 2; ++bj)
; #pragma unroll
;             for (int n = 0; n < 2; ++n) { const int c = colt + bj * HALF + n * 16;
;                 f32x4 gc = *(const f32x4*)(gain + c), sh = (f32x4){0.f, 0.f, 0.f, 0.f};
;                 if (!fin) { gc = gc * (*(const f32x4*)(mb + scoff + c) + 1.0f); sh = *(const f32x4*)(mb + shoff + c); }
; #pragma unroll
;                 for (int ai = 0; ai < 2; ++ai)
; #pragma unroll
;                     for (int m = 0; m < 4; ++m) { const int r = ai * HALF + wr * 64 + m * 16 + fr; const float rs = Sx[r];
;                         const f32x4 y = (acc[ai][bj][m][n] * rs) * gc + sh;
;                         if (fin) *(f32x4*)(xd + (size_t)(rowt + r) * D + c) = y;
;                         else { u32x2 w; w.x = cvt_pk_bf16(y[0], y[1]); w.y = cvt_pk_bf16(y[2], y[3]); *(u32x2*)(H + (size_t)(rowt + r) * D + c) = w; } } }
.LBB0_581:
	ds_read_b32 v8, v96 offset:4736
	s_mov_b64 s[6:7], -1
	s_and_b64 vcc, exec, s[84:85]
	s_waitcnt lgkmcnt(0)
	v_pk_mul_f32 v[6:7], v[6:7], v[8:9] op_sel_hi:[1,0]
	v_pk_mul_f32 v[4:5], v[4:5], v[8:9] op_sel_hi:[1,0]
	v_pk_fma_f32 v[6:7], v[34:35], v[6:7], v[38:39]
	v_pk_fma_f32 v[4:5], v[32:33], v[4:5], v[36:37]
	s_cbranch_vccz .LBB0_583
	v_add_u32_e32 v10, s8, v114
	v_ashrrev_i32_e32 v11, 31, v10
	v_readlane_b32 s0, v254, 35
	v_lshlrev_b64 v[10:11], 11, v[10:11]
	v_readlane_b32 s1, v254, 36
	v_cvt_pk_bf16_f32 v8, v4, v5
	v_cvt_pk_bf16_f32 v9, v6, v7
	s_mov_b64 s[6:7], 0
	s_nop 0
	v_lshl_add_u64 v[10:11], s[0:1], 0, v[10:11]
	v_lshl_add_u64 v[10:11], v[142:143], 1, v[10:11]
	v_mov_b64_e32 v[212:213], v[8:9]
	v_bfe_u32 v194, v196, 4, 1
	v_mov_b32_e32 v195, 0
	v_mul_u32_u24_e32 v194, 24, v194
	v_lshl_add_u64 v[10:11], v[10:11], 0, v[194:195]
	v_permlane16_swap_b32_e32 v210, v212
	v_permlane16_swap_b32_e32 v211, v213
	global_store_dwordx4 v[10:11], v[210:213], off offset:256

; __device__ __forceinline__ unsigned cvt_pk_bf16(float lo, float hi) { unsigned r; asm volatile("v_cvt_pk_bf16_f32 %0, %1, %2" : "=v"(r) : "v"(lo), "v"(hi)); return r; }
;     __device__ __forceinline__ void fused(f32x4 (&acc)[2][2][4][2], const Unit& u, int wr, int wc, int fr, int fq, ldsp lds, int wid, int lane) const {
;     ...
;         const int colt = u.pn * BM + wc * 32 + 4 * fq;
;         const float* mb = modn + (size_t)b * NMOD;
; #pragma unroll
;         for (int bj = 0; bj < 2; ++bj)
; #pragma unroll
;             for (int n = 0; n < 2; ++n) { const int c = colt + bj * HALF + n * 16;
;                 f32x4 gc = *(const f32x4*)(gain + c), sh = (f32x4){0.f, 0.f, 0.f, 0.f};
;                 if (!fin) { gc = gc * (*(const f32x4*)(mb + scoff + c) + 1.0f); sh = *(const f32x4*)(mb + shoff + c); }
; #pragma unroll
;                 for (int ai = 0; ai < 2; ++ai)
; #pragma unroll
;                     for (int m = 0; m < 4; ++m) { const int r = ai * HALF + wr * 64 + m * 16 + fr; const float rs = Sx[r];
;                         const f32x4 y = (acc[ai][bj][m][n] * rs) * gc + sh;
;                         if (fin) *(f32x4*)(xd + (size_t)(rowt + r) * D + c) = y;
;                         else { u32x2 w; w.x = cvt_pk_bf16(y[0], y[1]); w.y = cvt_pk_bf16(y[2], y[3]); *(u32x2*)(H + (size_t)(rowt + r) * D + c) = w; } } }
.LBB0_585:
	ds_read_b32 v4, v96 offset:4800
	s_mov_b64 s[6:7], -1
	s_and_b64 vcc, exec, s[84:85]
	s_waitcnt lgkmcnt(0)
	v_pk_mul_f32 v[2:3], v[2:3], v[4:5] op_sel_hi:[1,0]
	v_pk_mul_f32 v[0:1], v[0:1], v[4:5] op_sel_hi:[1,0]
	v_pk_fma_f32 v[2:3], v[34:35], v[2:3], v[38:39]
	v_pk_fma_f32 v[0:1], v[32:33], v[0:1], v[36:37]
	s_cbranch_vccz .LBB0_587
	v_add_u32_e32 v6, s8, v106
	v_ashrrev_i32_e32 v7, 31, v6
	v_readlane_b32 s0, v254, 35
	v_lshlrev_b64 v[6:7], 11, v[6:7]
	v_readlane_b32 s1, v254, 36
	v_cvt_pk_bf16_f32 v4, v0, v1
	v_cvt_pk_bf16_f32 v5, v2, v3
	s_mov_b64 s[6:7], 0
	s_nop 0
	v_lshl_add_u64 v[6:7], s[0:1], 0, v[6:7]
	v_lshl_add_u64 v[6:7], v[142:143], 1, v[6:7]
	v_mov_b64_e32 v[192:193], v[4:5]
	v_bfe_u32 v194, v196, 4, 1
	v_mov_b32_e32 v195, 0
	v_mul_u32_u24_e32 v194, 24, v194
	v_lshl_add_u64 v[6:7], v[6:7], 0, v[194:195]
	v_permlane16_swap_b32_e32 v190, v192
	v_permlane16_swap_b32_e32 v191, v193
	global_store_dwordx4 v[6:7], v[190:193], off offset:256
